# final-norm phase: all four rows loads issued before the first wait (ssq loads were waited one by one), loop-top vmcnt moved to the preheader
# speedup vs baseline: 1.0106x; 1.0069x over previous
.LBB0_1781:
	s_cmp_gt_i32 s92, 10
	s_cselect_b64 s[0:1], -1, 0
	s_cmp_lt_i32 s93, 10
	s_cselect_b64 s[2:3], -1, 0
	s_or_b64 s[0:1], s[0:1], s[2:3]
	s_and_b64 vcc, exec, s[0:1]
	s_cbranch_vccnz .LBB0_1851
	s_mov_b32 s14, 0x8000
	v_ashrrev_i32_e32 v0, 6, v224
	s_waitcnt vmcnt(3)
	v_lshl_add_u32 v50, s97, 3, v0
	v_cmp_gt_i32_e32 vcc, s14, v50
	s_and_saveexec_b64 s[0:1], vcc
	s_cbranch_execz .LBB0_1797
	v_readlane_b32 s16, v245, 33
	v_and_b32_e32 v18, 63, v224
	v_readlane_b32 s17, v245, 34
	v_lshlrev_b32_e32 v16, 4, v18
	v_readlane_b32 s18, v245, 35
	v_readlane_b32 s19, v245, 36
	s_mov_b64 s[4:5], s[16:17]
	s_waitcnt lgkmcnt(0)
	global_load_dwordx4 v[0:3], v16, s[4:5]
	global_load_dwordx4 v[4:7], v16, s[4:5] offset:1024
	global_load_dwordx4 v[8:11], v16, s[4:5] offset:2048
	global_load_dwordx4 v[12:15], v16, s[4:5] offset:3072
	v_mov_b32_e32 v17, 0
	s_lshl_b32 s8, s94, 3
	v_readlane_b32 s20, v245, 37
	s_mov_b64 s[6:7], s[18:19]
	v_lshlrev_b32_e32 v18, 3, v18
	v_mov_b32_e32 v19, v17
	s_add_i32 s19, s8, s8
	v_lshl_add_u64 v[18:19], s[78:79], 0, v[18:19]
	v_lshl_add_u64 v[20:21], s[6:7], 0, v[16:17]
	s_ashr_i32 s9, s8, 31
	s_lshl_b32 s15, s94, 4
	s_mul_i32 s16, s94, 24
	v_mov_b32_e32 v22, v17
	v_mov_b32_e32 v23, v17
	s_mov_b64 s[10:11], 0
	s_mov_b32 s17, 0x60000
	v_mov_b32_e32 v64, 0x358637bd
	s_mov_b32 s18, 0x800000
	s_add_i32 s19, s19, s8
	s_movk_i32 s20, 0x7fff
	v_readlane_b32 s21, v245, 38
	v_readlane_b32 s22, v245, 39
	v_readlane_b32 s23, v245, 40
	v_readlane_b32 s24, v245, 41
	v_readlane_b32 s25, v245, 42
	v_readlane_b32 s26, v245, 43
	v_readlane_b32 s27, v245, 44
	v_readlane_b32 s28, v245, 45
	v_readlane_b32 s29, v245, 46
	v_readlane_b32 s30, v245, 47
	v_readlane_b32 s31, v245, 48
	s_waitcnt vmcnt(5)
	s_branch .LBB0_1785

.LBB0_1785:
	v_ashrrev_i32_e32 v51, 31, v50
	v_lshl_add_u64 v[52:53], v[50:51], 2, s[84:85]
	v_add_co_u32_e32 v48, vcc, s17, v52
	s_nop 1
	v_addc_co_u32_e32 v49, vcc, 0, v53, vcc
	global_load_dword v16, v[48:49], off
	v_lshlrev_b64 v[48:49], 11, v[50:51]
	v_lshl_add_u64 v[48:49], v[18:19], 0, v[48:49]
	global_load_dwordx2 v[62:63], v[48:49], off nt
	global_load_dwordx2 v[60:61], v[48:49], off offset:512 nt
	global_load_dwordx2 v[58:59], v[48:49], off offset:1024 nt
	global_load_dwordx2 v[56:57], v[48:49], off offset:1536 nt
	v_add_u32_e32 v48, s8, v50
	v_cmp_gt_i32_e64 s[6:7], s14, v48
	v_ashrrev_i32_e32 v49, 31, v48
	s_and_saveexec_b64 s[2:3], s[6:7]
	s_cbranch_execz .LBB0_1787
	v_lshl_add_u64 v[40:41], s[8:9], 2, v[52:53]
	v_add_co_u32_e32 v40, vcc, 0x60000, v40
	s_nop 1
	v_addc_co_u32_e32 v41, vcc, 0, v41, vcc
	global_load_dword v17, v[40:41], off
	v_lshlrev_b64 v[40:41], 11, v[48:49]
	v_lshl_add_u64 v[52:53], v[18:19], 0, v[40:41]
	global_load_dwordx2 v[46:47], v[52:53], off nt
	global_load_dwordx2 v[44:45], v[52:53], off offset:512 nt
	global_load_dwordx2 v[42:43], v[52:53], off offset:1024 nt
	global_load_dwordx2 v[40:41], v[52:53], off offset:1536 nt
.LBB0_1787:
	s_or_b64 exec, exec, s[2:3]
	v_add_u32_e32 v54, s15, v50
	v_cmp_gt_i32_e64 s[4:5], s14, v54
	v_ashrrev_i32_e32 v55, 31, v54
	s_and_saveexec_b64 s[2:3], s[4:5]
	s_cbranch_execz .LBB0_1789
	v_lshl_add_u64 v[32:33], v[54:55], 2, s[84:85]
	v_add_co_u32_e32 v32, vcc, 0x60000, v32
	s_nop 1
	v_addc_co_u32_e32 v33, vcc, 0, v33, vcc
	global_load_dword v22, v[32:33], off
	v_lshlrev_b64 v[32:33], 11, v[54:55]
	v_lshl_add_u64 v[52:53], v[18:19], 0, v[32:33]
	global_load_dwordx2 v[38:39], v[52:53], off nt
	global_load_dwordx2 v[36:37], v[52:53], off offset:512 nt
	global_load_dwordx2 v[34:35], v[52:53], off offset:1024 nt
	global_load_dwordx2 v[32:33], v[52:53], off offset:1536 nt
.LBB0_1789:
	s_or_b64 exec, exec, s[2:3]
	v_add_u32_e32 v52, s16, v50
	v_cmp_gt_i32_e64 s[2:3], s14, v52
	v_ashrrev_i32_e32 v53, 31, v52
	s_and_saveexec_b64 s[12:13], s[2:3]
	s_cbranch_execz .LBB0_1791
	v_lshl_add_u64 v[24:25], v[52:53], 2, s[84:85]
	v_add_co_u32_e32 v24, vcc, 0x60000, v24
	s_nop 1
	v_addc_co_u32_e32 v25, vcc, 0, v25, vcc
	global_load_dword v23, v[24:25], off
	v_lshlrev_b64 v[24:25], 11, v[52:53]
	v_lshl_add_u64 v[66:67], v[18:19], 0, v[24:25]
	global_load_dwordx2 v[30:31], v[66:67], off nt
	global_load_dwordx2 v[28:29], v[66:67], off offset:512 nt
	global_load_dwordx2 v[26:27], v[66:67], off offset:1024 nt
	global_load_dwordx2 v[24:25], v[66:67], off offset:1536 nt
.LBB0_1791:
	s_or_b64 exec, exec, s[12:13]
	s_waitcnt vmcnt(4)
	v_fmamk_f32 v16, v16, 0x3a800000, v64
	v_mul_f32_e32 v70, 0x4b800000, v16
	v_cmp_gt_f32_e32 vcc, s18, v16
	s_nop 1
	v_cndmask_b32_e32 v16, v16, v70, vcc
	v_rsq_f32_e32 v16, v16
	s_nop 0
	v_mul_f32_e32 v70, 0x45800000, v16
	v_cndmask_b32_e32 v16, v16, v70, vcc
	v_fmamk_f32 v17, v17, 0x3a800000, v64
	v_mul_f32_e32 v72, 0x4b800000, v17
	v_cmp_gt_f32_e32 vcc, s18, v17
	s_nop 1
	v_cndmask_b32_e32 v17, v17, v72, vcc
	v_rsq_f32_e32 v17, v17
	s_nop 0
	v_mul_f32_e32 v72, 0x45800000, v17
	v_cndmask_b32_e32 v17, v17, v72, vcc
	v_fmamk_f32 v22, v22, 0x3a800000, v64
	v_mul_f32_e32 v73, 0x4b800000, v22
	v_cmp_gt_f32_e32 vcc, s18, v22
	s_nop 1
	v_cndmask_b32_e32 v22, v22, v73, vcc
	v_rsq_f32_e32 v22, v22
	s_nop 0
	v_mul_f32_e32 v73, 0x45800000, v22
	v_cndmask_b32_e32 v22, v22, v73, vcc
	v_fmamk_f32 v23, v23, 0x3a800000, v64
	v_mul_f32_e32 v74, 0x4b800000, v23
	v_cmp_gt_f32_e32 vcc, s18, v23
	s_nop 1
	v_cndmask_b32_e32 v23, v23, v74, vcc
	v_rsq_f32_e32 v23, v23
	s_nop 0
	v_mul_f32_e32 v74, 0x45800000, v23
	v_cndmask_b32_e32 v23, v23, v74, vcc
	s_waitcnt vmcnt(3)
	v_lshlrev_b32_e32 v66, 16, v62
	v_and_b32_e32 v67, 0xffff0000, v62
	v_lshlrev_b32_e32 v62, 16, v63
	v_and_b32_e32 v63, 0xffff0000, v63
	v_lshlrev_b64 v[50:51], 12, v[50:51]
	v_pk_mul_f32 v[66:67], v[16:17], v[66:67] op_sel_hi:[0,1]
	v_pk_mul_f32 v[62:63], v[16:17], v[62:63] op_sel_hi:[0,1]
	v_lshl_add_u64 v[50:51], v[20:21], 0, v[50:51]
	v_pk_mul_f32 v[68:69], v[2:3], v[62:63]
	v_pk_mul_f32 v[66:67], v[0:1], v[66:67]
	s_waitcnt vmcnt(2)
	v_lshlrev_b32_e32 v62, 16, v60
	v_and_b32_e32 v63, 0xffff0000, v60
	v_lshlrev_b32_e32 v60, 16, v61
	v_and_b32_e32 v61, 0xffff0000, v61
	global_store_dwordx4 v[50:51], v[66:69], off nt
	v_pk_mul_f32 v[60:61], v[16:17], v[60:61] op_sel_hi:[0,1]
	s_nop 0
	v_pk_mul_f32 v[66:67], v[16:17], v[62:63] op_sel_hi:[0,1]
	v_pk_mul_f32 v[62:63], v[6:7], v[60:61]
	v_pk_mul_f32 v[60:61], v[4:5], v[66:67]
	global_store_dwordx4 v[50:51], v[60:63], off offset:1024 nt
	s_waitcnt vmcnt(3)
	s_nop 0
	v_lshlrev_b32_e32 v60, 16, v58
	v_and_b32_e32 v61, 0xffff0000, v58
	v_lshlrev_b32_e32 v58, 16, v59
	v_and_b32_e32 v59, 0xffff0000, v59
	v_pk_mul_f32 v[62:63], v[16:17], v[60:61] op_sel_hi:[0,1]
	v_pk_mul_f32 v[58:59], v[16:17], v[58:59] op_sel_hi:[0,1]
	v_pk_mul_f32 v[60:61], v[10:11], v[58:59]
	v_pk_mul_f32 v[58:59], v[8:9], v[62:63]
	global_store_dwordx4 v[50:51], v[58:61], off offset:2048 nt
	s_waitcnt vmcnt(3)
	s_nop 0
	v_lshlrev_b32_e32 v58, 16, v56
	v_and_b32_e32 v59, 0xffff0000, v56
	v_lshlrev_b32_e32 v56, 16, v57
	v_and_b32_e32 v57, 0xffff0000, v57
	v_pk_mul_f32 v[60:61], v[16:17], v[58:59] op_sel_hi:[0,1]
	v_pk_mul_f32 v[56:57], v[16:17], v[56:57] op_sel_hi:[0,1]
	v_pk_mul_f32 v[58:59], v[14:15], v[56:57]
	v_pk_mul_f32 v[56:57], v[12:13], v[60:61]
	global_store_dwordx4 v[50:51], v[56:59], off offset:3072 nt
	s_and_saveexec_b64 s[12:13], s[6:7]
	s_cbranch_execnz .LBB0_1794
	s_or_b64 exec, exec, s[12:13]
	s_and_saveexec_b64 s[6:7], s[4:5]
	s_cbranch_execnz .LBB0_1795
